# pipelined attention v12: PV k-steps 0,1 moved to the end of the softmax block (blocks rebalanced), l-sum in those MFMA gaps
# baseline (speedup 1.0000x reference)
; #define MFMA32(a, b, c) __builtin_amdgcn_mfma_f32_32x32x16_bf16((a), (b), (c), 0, 0, 0)
; DI unsigned pk2(float a, float b) { f32x2 v = {a, b}; return __builtin_bit_cast(unsigned, __builtin_convertvector(v, bfv2)); }
; DI void attn_s(const unsigned char* sK, int tt, int qb, int qs, int sub, int l31, int h,
;                const bf16x8 (&qf)[4], f32x16 (&O)[4], float& m, float& l, bf16x8 (&pb)[4]) {
;     ...
; #pragma unroll
;     for (int k2 = 0; k2 < 2; ++k2)
; #pragma unroll
;         for (int i = 0; i < 16; ++i) st[k2][i] = __builtin_amdgcn_exp2f(st[k2][i]);
;     {
;         const f32x16 sv = st[0] + st[1];
;         const float ps = (((sv[0] + sv[1]) + (sv[2] + sv[3])) + ((sv[4] + sv[5]) + (sv[6] + sv[7]))) + (((sv[8] + sv[9]) + (sv[10] + sv[11])) + ((sv[12] + sv[13]) + (sv[14] + sv[15])));
;         l += ps;
;     }
; #pragma unroll
;     for (int k4 = 0; k4 < 4; ++k4) {
;         const int k2 = k4 >> 1, o8 = 8 * (k4 & 1);
;         u32x4 pk;
;         pk.x = pk2(st[k2][o8 + 0], st[k2][o8 + 1]); pk.y = pk2(st[k2][o8 + 2], st[k2][o8 + 3]);
;         pk.z = pk2(st[k2][o8 + 4], st[k2][o8 + 5]); pk.w = pk2(st[k2][o8 + 6], st[k2][o8 + 7]);
;         pb[k4] = __builtin_bit_cast(bf16x8, pk);
;     }
; DI void attn_pv(const unsigned char* sV, int l31, int h, const bf16x8 (&pb)[4], f32x16 (&O)[4]) {
;     ...
;         for (int d = 0; d < 4; ++d) O[d] = MFMA32(va[d], pb[0], O[d]);
;         __builtin_amdgcn_sched_barrier(0);
; #pragma unroll
;         for (int d = 0; d < 4; ++d) va[d] = *(const bf16x8*)(vb + d * 32 * A_VROWB + 64);
;         __builtin_amdgcn_sched_barrier(0);
; #pragma unroll
;         for (int d = 0; d < 4; ++d) O[d] = MFMA32(vc[d], pb[1], O[d]);
;         __builtin_amdgcn_sched_barrier(0);
; #pragma unroll
;         for (int d = 0; d < 4; ++d) vc[d] = *(const bf16x8*)(vb + d * 32 * A_VROWB + 96);
;         __builtin_amdgcn_sched_barrier(0);
; #pragma unroll
;         for (int d = 0; d < 4; ++d) O[d] = MFMA32(va[d], pb[2], O[d]);
;         __builtin_amdgcn_sched_barrier(0);
; #pragma unroll
;         for (int d = 0; d < 4; ++d) O[d] = MFMA32(vc[d], pb[3], O[d]);
.Lpipe_norescale_l:
	v_exp_f32_e32 v66, v66
	v_exp_f32_e32 v67, v67
	v_exp_f32_e32 v68, v68
	v_exp_f32_e32 v69, v69
	v_exp_f32_e32 v70, v70
	v_exp_f32_e32 v71, v71
	v_exp_f32_e32 v72, v72
	v_exp_f32_e32 v73, v73
	v_exp_f32_e32 v74, v74
	v_exp_f32_e32 v75, v75
	v_exp_f32_e32 v76, v76
	v_exp_f32_e32 v77, v77
	v_exp_f32_e32 v78, v78
	v_exp_f32_e32 v79, v79
	v_exp_f32_e32 v80, v80
	v_exp_f32_e32 v81, v81
	v_cvt_pk_bf16_f32 v216, v82, v83
	v_cvt_pk_bf16_f32 v217, v84, v85
	v_cvt_pk_bf16_f32 v218, v86, v87
	v_cvt_pk_bf16_f32 v219, v88, v89
	v_cvt_pk_bf16_f32 v220, v90, v91
	v_cvt_pk_bf16_f32 v221, v92, v93
	v_cvt_pk_bf16_f32 v222, v94, v95
	v_cvt_pk_bf16_f32 v223, v96, v97
	v_cvt_pk_bf16_f32 v224, v66, v67
	v_cvt_pk_bf16_f32 v225, v68, v69
	v_cvt_pk_bf16_f32 v226, v70, v71
	v_cvt_pk_bf16_f32 v227, v72, v73
	v_cvt_pk_bf16_f32 v228, v74, v75
	v_cvt_pk_bf16_f32 v229, v76, v77
	v_cvt_pk_bf16_f32 v230, v78, v79
	v_cvt_pk_bf16_f32 v231, v80, v81
	ds_read_b128 v[160:163], v191 offset:17472
	ds_read_b128 v[164:167], v191 offset:22080
	ds_read_b128 v[168:171], v191 offset:26688
	ds_read_b128 v[196:199], v191 offset:31296
	s_waitcnt lgkmcnt(11)
	v_mfma_f32_32x32x16_bf16 v[50:65], v[172:175], v[216:219], v[50:65]
	v_pk_add_f32 v[68:69], v[84:85], v[68:69]
	v_pk_add_f32 v[66:67], v[82:83], v[66:67]
	v_pk_add_f32 v[72:73], v[88:89], v[72:73]
	s_waitcnt lgkmcnt(10)
	v_mfma_f32_32x32x16_bf16 v[34:49], v[176:179], v[216:219], v[34:49]
	v_pk_add_f32 v[70:71], v[86:87], v[70:71]
	v_add_f32_e32 v66, v66, v67
	v_add_f32_e32 v67, v68, v69
	s_waitcnt lgkmcnt(9)
	v_mfma_f32_32x32x16_bf16 v[18:33], v[180:183], v[216:219], v[18:33]
	v_add_f32_e32 v66, v66, v67
	v_add_f32_e32 v67, v70, v71
	v_add_f32_e32 v68, v72, v73
	s_waitcnt lgkmcnt(8)
	v_mfma_f32_32x32x16_bf16 v[2:17], v[192:195], v[216:219], v[2:17]
	v_pk_add_f32 v[76:77], v[92:93], v[76:77]
	v_pk_add_f32 v[74:75], v[90:91], v[74:75]
	v_add_f32_e32 v67, v67, v68
	s_waitcnt lgkmcnt(7)
	v_mfma_f32_32x32x16_bf16 v[50:65], v[200:203], v[220:223], v[50:65]
	v_pk_add_f32 v[80:81], v[96:97], v[80:81]
	v_pk_add_f32 v[78:79], v[94:95], v[78:79]
	v_add_f32_e32 v66, v66, v67
	v_add_f32_e32 v67, v74, v75
	s_waitcnt lgkmcnt(6)
	v_mfma_f32_32x32x16_bf16 v[34:49], v[204:207], v[220:223], v[34:49]
	v_add_f32_e32 v68, v76, v77
	v_add_f32_e32 v67, v67, v68
	v_add_f32_e32 v68, v78, v79
	v_add_f32_e32 v69, v80, v81
	s_waitcnt lgkmcnt(5)
	v_mfma_f32_32x32x16_bf16 v[18:33], v[208:211], v[220:223], v[18:33]
	v_add_f32_e32 v68, v68, v69
	v_add_f32_e32 v67, v67, v68
	v_add_f32_e32 v66, v66, v67
	v_add_f32_e32 v1, v1, v66
	s_waitcnt lgkmcnt(4)
	v_mfma_f32_32x32x16_bf16 v[2:17], v[212:215], v[220:223], v[2:17]
	v_add_u32_e32 v158, 64, v158
	s_mov_b32 s13, s7
	s_add_i32 s4, s7, 1
	s_cmp_lg_u32 s7, 2
	s_cselect_b32 s7, s4, 0
	s_add_i32 s12, s12, 1
	s_cmp_eq_u32 s11, s12
	s_cbranch_scc1 .Lpipe_final
	s_barrier
	s_setprio 1
	s_mul_i32 s98, s13, 0x8c00
	v_add3_u32 v185, s98, v155, v154
	ds_read_b128 v[172:175], v185
	ds_read_b128 v[176:179], v185 offset:32
	ds_read_b128 v[180:183], v185 offset:8704
	ds_read_b128 v[192:195], v185 offset:8736
	ds_read_b128 v[200:203], v185 offset:64
	ds_read_b128 v[204:207], v185 offset:96
	ds_read_b128 v[208:211], v185 offset:8768
	ds_read_b128 v[212:215], v185 offset:8800
	s_waitcnt lgkmcnt(11)
	v_mfma_f32_32x32x16_bf16 v[50:65], v[160:163], v[224:227], v[50:65]
	s_waitcnt lgkmcnt(10)
	v_mfma_f32_32x32x16_bf16 v[34:49], v[164:167], v[224:227], v[34:49]
	s_waitcnt lgkmcnt(9)
	v_mfma_f32_32x32x16_bf16 v[18:33], v[168:171], v[224:227], v[18:33]
	s_waitcnt lgkmcnt(8)
	v_mfma_f32_32x32x16_bf16 v[2:17], v[196:199], v[224:227], v[2:17]
	ds_read_b128 v[160:163], v191 offset:17504
	ds_read_b128 v[164:167], v191 offset:22112
	ds_read_b128 v[168:171], v191 offset:26720
	ds_read_b128 v[196:199], v191 offset:31328
	s_waitcnt lgkmcnt(11)
	v_mfma_f32_32x32x16_bf16 v[82:97], v[172:175], v[100:103], v[240:255]
	s_waitcnt lgkmcnt(9)
	v_mfma_f32_32x32x16_bf16 v[66:81], v[180:183], v[100:103], v[240:255]
	v_mfma_f32_32x32x16_bf16 v[82:97], v[176:179], v[104:107], v[82:97]
	s_waitcnt lgkmcnt(8)
	v_mfma_f32_32x32x16_bf16 v[66:81], v[192:195], v[104:107], v[66:81]
	s_waitcnt lgkmcnt(7)
	v_mfma_f32_32x32x16_bf16 v[82:97], v[200:203], v[108:111], v[82:97]
	s_waitcnt lgkmcnt(5)
	v_mfma_f32_32x32x16_bf16 v[66:81], v[208:211], v[108:111], v[66:81]
	v_mfma_f32_32x32x16_bf16 v[82:97], v[204:207], v[112:115], v[82:97]
	s_waitcnt lgkmcnt(4)
	v_mfma_f32_32x32x16_bf16 v[66:81], v[212:215], v[112:115], v[66:81]
	s_add_i32 s14, s12, 0x42
	s_cmp_ge_i32 s14, s6
	s_cbranch_scc1 .Lpipe_nost_l
	s_mul_i32 s4, s7, 0x8c00
	s_add_i32 s4, s4, 0
	v_add_u32_e32 v184, s4, v140
	v_add_u32_e32 v185, v184, v139
	v_add_u32_e32 v184, v184, v141
	s_waitcnt vmcnt(3)
	ds_write_b128 v185, v[116:119]
	s_waitcnt vmcnt(2)
	ds_write_b128 v184, v[120:123]
	v_add3_u32 v184, s4, v150, v151
	v_add_u32_e32 v185, v184, v152
	v_add_u32_e32 v184, v184, v153
	v_add_u32_e32 v185, 0x4000, v185
	v_add_u32_e32 v184, 0x4000, v184
	s_waitcnt vmcnt(1)
	ds_write2_b64 v185, v[124:125], v[126:127] offset0:128 offset1:130
	s_waitcnt vmcnt(0)
	ds_write2_b64 v184, v[128:129], v[130:131] offset0:128 offset1:130

; #define MFMA32(a, b, c) __builtin_amdgcn_mfma_f32_32x32x16_bf16((a), (b), (c), 0, 0, 0)
; DI void attn_pv(const unsigned char* sV, int l31, int h, const bf16x8 (&pb)[4], f32x16 (&O)[4]) {
;     ...
;         for (int d = 0; d < 4; ++d) O[d] = MFMA32(va[d], pb[0], O[d]);
;         __builtin_amdgcn_sched_barrier(0);
; #pragma unroll
;         for (int d = 0; d < 4; ++d) va[d] = *(const bf16x8*)(vb + d * 32 * A_VROWB + 64);
;         __builtin_amdgcn_sched_barrier(0);
; #pragma unroll
;         for (int d = 0; d < 4; ++d) O[d] = MFMA32(vc[d], pb[1], O[d]);
;         __builtin_amdgcn_sched_barrier(0);
; #pragma unroll
;         for (int d = 0; d < 4; ++d) vc[d] = *(const bf16x8*)(vb + d * 32 * A_VROWB + 96);
;         __builtin_amdgcn_sched_barrier(0);
; #pragma unroll
;         for (int d = 0; d < 4; ++d) O[d] = MFMA32(va[d], pb[2], O[d]);
;         __builtin_amdgcn_sched_barrier(0);
; #pragma unroll
;         for (int d = 0; d < 4; ++d) O[d] = MFMA32(vc[d], pb[3], O[d]);
.Lpipe_nopf_l:
	s_waitcnt lgkmcnt(3)
	v_mfma_f32_32x32x16_bf16 v[50:65], v[160:163], v[228:231], v[50:65]
	s_waitcnt lgkmcnt(2)
	v_mfma_f32_32x32x16_bf16 v[34:49], v[164:167], v[228:231], v[34:49]
	s_waitcnt lgkmcnt(1)
	v_mfma_f32_32x32x16_bf16 v[18:33], v[168:171], v[228:231], v[18:33]
	s_waitcnt lgkmcnt(0)
	v_mfma_f32_32x32x16_bf16 v[2:17], v[196:199], v[228:231], v[2:17]
	s_setprio 0
	s_waitcnt lgkmcnt(0)
	s_barrier
	s_branch .Lpipe_loop
.Lpipe_final:
	s_barrier
	s_waitcnt lgkmcnt(3)
	v_mfma_f32_32x32x16_bf16 v[50:65], v[160:163], v[224:227], v[50:65]
	s_waitcnt lgkmcnt(2)
	v_mfma_f32_32x32x16_bf16 v[34:49], v[164:167], v[224:227], v[34:49]
	s_waitcnt lgkmcnt(1)
	v_mfma_f32_32x32x16_bf16 v[18:33], v[168:171], v[224:227], v[18:33]
	s_waitcnt lgkmcnt(0)
	v_mfma_f32_32x32x16_bf16 v[2:17], v[196:199], v[224:227], v[2:17]
	ds_read_b128 v[172:175], v191 offset:17504
	ds_read_b128 v[176:179], v191 offset:22112
	ds_read_b128 v[180:183], v191 offset:26720
	ds_read_b128 v[192:195], v191 offset:31328
	s_waitcnt lgkmcnt(3)
	v_mfma_f32_32x32x16_bf16 v[50:65], v[172:175], v[228:231], v[50:65]
	s_waitcnt lgkmcnt(2)
	v_mfma_f32_32x32x16_bf16 v[34:49], v[176:179], v[228:231], v[34:49]
	s_waitcnt lgkmcnt(1)
	v_mfma_f32_32x32x16_bf16 v[18:33], v[180:183], v[228:231], v[18:33]
	s_waitcnt lgkmcnt(0)
	v_mfma_f32_32x32x16_bf16 v[2:17], v[192:195], v[228:231], v[2:17]
	s_barrier
	s_cmp_eq_u32 s99, 1
	s_cbranch_scc1 .Lpipe_done
	s_barrier
